# seam conversion: transposed LDS tile with 66-float pitch, reads as 4 ds_read_b64 per row group (conflict-free) instead of 32 ds_read_b32
# baseline (speedup 1.0000x reference)
.LBB0_253:
	s_cmp_gt_i32 s29, 1
	s_cselect_b64 s[0:1], -1, 0
	s_and_b64 s[4:5], s[60:61], s[0:1]
	s_andn2_b64 vcc, exec, s[4:5]
	s_cbranch_vccnz .LBB0_303
	s_waitcnt vmcnt(0)
	v_cmp_eq_u32_e32 vcc, 0, v208
	s_waitcnt lgkmcnt(0)
	s_barrier
	v_readfirstlane_b32 s3, v208
	s_nop 3
	s_lshr_b32 s3, s3, 6
	s_cmp_eq_u32 s3, 0
	s_cbranch_scc1 .Lmy_cv0_end
	v_readlane_b32 s36, v237, 0
	v_readlane_b32 s37, v237, 1
	s_mul_i32 s4, s2, 7
	s_add_i32 s4, s4, s3
	s_add_i32 s4, s4, -1
	s_lshl_b32 s72, s3, 14
	s_mov_b32 s3, s4
	s_nop 4
	s_load_dwordx4 s[60:63], s[36:37], 0x60
	s_load_dwordx2 s[64:65], s[36:37], 0x70
	s_load_dwordx2 s[98:99], s[36:37], 0x58
	s_load_dwordx2 s[100:101], s[36:37], 0x48
	v_lshrrev_b32_e32 v6, 5, v209
	v_and_b32_e32 v7, 31, v209
	v_mul_u32_u24_e32 v0, 0x1600, v6
	v_add_lshl_u32 v0, v0, v7, 2
	v_lshlrev_b32_e32 v152, 11, v6
	v_add_lshl_u32 v152, v152, v7, 2
	v_mul_u32_u24_e32 v2, 66, v7
	v_add_lshl_u32 v2, v2, v6, 2
	v_add_u32_e32 v2, s72, v2
	v_and_b32_e32 v8, 7, v209
	v_lshrrev_b32_e32 v9, 3, v209
	v_mul_u32_u24_e32 v3, 0x108, v9
	v_lshl_add_u32 v3, v8, 5, v3
	v_add_u32_e32 v3, s72, v3
	v_lshlrev_b32_e32 v4, 12, v9
	v_lshl_add_u32 v4, v8, 4, v4
	v_lshlrev_b32_e32 v5, 5, v8
	s_waitcnt lgkmcnt(0)
	s_add_i32 s66, s3, 256
	s_lshr_b32 vcc_lo, s66, 6
	s_and_b32 vcc_hi, s66, 63
	s_lshl_b32 s70, vcc_lo, 19
	s_lshl_b32 s71, vcc_hi, 7
	s_add_u32 s68, s98, s70
	s_addc_u32 s69, s99, 0
	s_add_u32 s68, s68, s71
	s_addc_u32 s69, s69, 0
	v_mov_b32_e32 v1, v152
	global_load_dword v112, v1, s[68:69] nt
	v_add_u32_e32 v1, 0x4000, v1
	global_load_dword v113, v1, s[68:69] nt
	v_add_u32_e32 v1, 0x4000, v1
	global_load_dword v114, v1, s[68:69] nt
	v_add_u32_e32 v1, 0x4000, v1
	global_load_dword v115, v1, s[68:69] nt
	v_add_u32_e32 v1, 0x4000, v1
	global_load_dword v116, v1, s[68:69] nt
	v_add_u32_e32 v1, 0x4000, v1
	global_load_dword v117, v1, s[68:69] nt
	v_add_u32_e32 v1, 0x4000, v1
	global_load_dword v118, v1, s[68:69] nt
	v_add_u32_e32 v1, 0x4000, v1
	global_load_dword v119, v1, s[68:69] nt
	v_add_u32_e32 v1, 0x4000, v1
	global_load_dword v120, v1, s[68:69] nt
	v_add_u32_e32 v1, 0x4000, v1
	global_load_dword v121, v1, s[68:69] nt
	v_add_u32_e32 v1, 0x4000, v1
	global_load_dword v122, v1, s[68:69] nt
	v_add_u32_e32 v1, 0x4000, v1
	global_load_dword v123, v1, s[68:69] nt
	v_add_u32_e32 v1, 0x4000, v1
	global_load_dword v124, v1, s[68:69] nt
	v_add_u32_e32 v1, 0x4000, v1
	global_load_dword v125, v1, s[68:69] nt
	v_add_u32_e32 v1, 0x4000, v1
	global_load_dword v126, v1, s[68:69] nt
	v_add_u32_e32 v1, 0x4000, v1
	global_load_dword v127, v1, s[68:69] nt
	v_add_u32_e32 v1, 0x4000, v1
	global_load_dword v128, v1, s[68:69] nt
	v_add_u32_e32 v1, 0x4000, v1
	global_load_dword v129, v1, s[68:69] nt
	v_add_u32_e32 v1, 0x4000, v1
	global_load_dword v130, v1, s[68:69] nt
	v_add_u32_e32 v1, 0x4000, v1
	global_load_dword v131, v1, s[68:69] nt
	v_add_u32_e32 v1, 0x4000, v1
	global_load_dword v132, v1, s[68:69] nt
	v_add_u32_e32 v1, 0x4000, v1
	global_load_dword v133, v1, s[68:69] nt
	v_add_u32_e32 v1, 0x4000, v1
	global_load_dword v134, v1, s[68:69] nt
	v_add_u32_e32 v1, 0x4000, v1
	global_load_dword v135, v1, s[68:69] nt
	v_add_u32_e32 v1, 0x4000, v1
	global_load_dword v136, v1, s[68:69] nt
	v_add_u32_e32 v1, 0x4000, v1
	global_load_dword v137, v1, s[68:69] nt
	v_add_u32_e32 v1, 0x4000, v1
	global_load_dword v138, v1, s[68:69] nt
	v_add_u32_e32 v1, 0x4000, v1
	global_load_dword v139, v1, s[68:69] nt
	v_add_u32_e32 v1, 0x4000, v1
	global_load_dword v140, v1, s[68:69] nt
	v_add_u32_e32 v1, 0x4000, v1
	global_load_dword v141, v1, s[68:69] nt
	v_add_u32_e32 v1, 0x4000, v1
	global_load_dword v142, v1, s[68:69] nt
	v_add_u32_e32 v1, 0x4000, v1
	global_load_dword v143, v1, s[68:69] nt
	s_and_b32 s70, vcc_lo, 1
	s_lshl_b32 s70, s70, 8
	s_add_u32 s70, s100, s70
	s_addc_u32 s71, s101, 0
	global_load_dwordx4 v[144:147], v5, s[70:71]
	global_load_dwordx4 v[148:151], v5, s[70:71] offset:16
	s_add_i32 s66, s3, 512
	s_cmpk_ge_u32 s66, 0x1600
	s_cselect_b32 s68, s64, s62
	s_cselect_b32 s69, s65, s63
	s_cselect_b32 s54, 128, 0
	s_cselect_b32 s41, 0x1600, 0
	s_sub_u32 s41, s66, s41
	s_mul_hi_u32 s4, s41, 0xba2e8ba3
	s_lshr_b32 s4, s4, 7
	s_mul_i32 s70, s4, 0xb0
	s_sub_u32 s5, s41, s70
	s_mul_i32 s70, s4, 0x160000
	s_lshl_b32 s71, s5, 7
	s_add_u32 s68, s68, s70
	s_addc_u32 s69, s69, 0
	s_add_u32 s68, s68, s71
	s_addc_u32 s69, s69, 0
	v_mov_b32_e32 v1, v0
	global_load_dword v32, v1, s[68:69] nt
	v_add_u32_e32 v1, 0xb000, v1
	global_load_dword v33, v1, s[68:69] nt
	v_add_u32_e32 v1, 0xb000, v1
	global_load_dword v34, v1, s[68:69] nt
	v_add_u32_e32 v1, 0xb000, v1
	global_load_dword v35, v1, s[68:69] nt
	v_add_u32_e32 v1, 0xb000, v1
	global_load_dword v36, v1, s[68:69] nt
	v_add_u32_e32 v1, 0xb000, v1
	global_load_dword v37, v1, s[68:69] nt
	v_add_u32_e32 v1, 0xb000, v1
	global_load_dword v38, v1, s[68:69] nt
	v_add_u32_e32 v1, 0xb000, v1
	global_load_dword v39, v1, s[68:69] nt
	v_add_u32_e32 v1, 0xb000, v1
	global_load_dword v40, v1, s[68:69] nt
	v_add_u32_e32 v1, 0xb000, v1
	global_load_dword v41, v1, s[68:69] nt
	v_add_u32_e32 v1, 0xb000, v1
	global_load_dword v42, v1, s[68:69] nt
	v_add_u32_e32 v1, 0xb000, v1
	global_load_dword v43, v1, s[68:69] nt
	v_add_u32_e32 v1, 0xb000, v1
	global_load_dword v44, v1, s[68:69] nt
	v_add_u32_e32 v1, 0xb000, v1
	global_load_dword v45, v1, s[68:69] nt
	v_add_u32_e32 v1, 0xb000, v1
	global_load_dword v46, v1, s[68:69] nt
	v_add_u32_e32 v1, 0xb000, v1
	global_load_dword v47, v1, s[68:69] nt
	v_add_u32_e32 v1, 0xb000, v1
	global_load_dword v48, v1, s[68:69] nt
	v_add_u32_e32 v1, 0xb000, v1
	global_load_dword v49, v1, s[68:69] nt
	v_add_u32_e32 v1, 0xb000, v1
	global_load_dword v50, v1, s[68:69] nt
	v_add_u32_e32 v1, 0xb000, v1
	global_load_dword v51, v1, s[68:69] nt
	v_add_u32_e32 v1, 0xb000, v1
	global_load_dword v52, v1, s[68:69] nt
	v_add_u32_e32 v1, 0xb000, v1
	global_load_dword v53, v1, s[68:69] nt
	v_add_u32_e32 v1, 0xb000, v1
	global_load_dword v54, v1, s[68:69] nt
	v_add_u32_e32 v1, 0xb000, v1
	global_load_dword v55, v1, s[68:69] nt
	v_add_u32_e32 v1, 0xb000, v1
	global_load_dword v56, v1, s[68:69] nt
	v_add_u32_e32 v1, 0xb000, v1
	global_load_dword v57, v1, s[68:69] nt
	v_add_u32_e32 v1, 0xb000, v1
	global_load_dword v58, v1, s[68:69] nt
	v_add_u32_e32 v1, 0xb000, v1
	global_load_dword v59, v1, s[68:69] nt
	v_add_u32_e32 v1, 0xb000, v1
	global_load_dword v60, v1, s[68:69] nt
	v_add_u32_e32 v1, 0xb000, v1
	global_load_dword v61, v1, s[68:69] nt
	v_add_u32_e32 v1, 0xb000, v1
	global_load_dword v62, v1, s[68:69] nt
	v_add_u32_e32 v1, 0xb000, v1
	global_load_dword v63, v1, s[68:69] nt
	s_lshl_b32 s70, s4, 8
	s_add_u32 s70, s60, s70
	s_addc_u32 s71, s61, 0
	global_load_dwordx4 v[96:99], v5, s[70:71]
	global_load_dwordx4 v[100:103], v5, s[70:71] offset:16
	s_addk_i32 s66, 0x700
	s_cmpk_ge_u32 s66, 0x1600
	s_cselect_b32 s68, s64, s62
	s_cselect_b32 s69, s65, s63
	s_cselect_b32 s40, 128, 0
	s_cselect_b32 s41, 0x1600, 0
	s_sub_u32 s41, s66, s41
	s_mul_hi_u32 s55, s41, 0xba2e8ba3
	s_lshr_b32 s55, s55, 7
	s_mul_i32 s70, s55, 0xb0
	s_sub_u32 s67, s41, s70
	s_mul_i32 s70, s55, 0x160000
	s_lshl_b32 s71, s67, 7
	s_add_u32 s68, s68, s70
	s_addc_u32 s69, s69, 0
	s_add_u32 s68, s68, s71
	s_addc_u32 s69, s69, 0
	v_mov_b32_e32 v1, v0
	global_load_dword v64, v1, s[68:69] nt
	v_add_u32_e32 v1, 0xb000, v1
	global_load_dword v65, v1, s[68:69] nt
	v_add_u32_e32 v1, 0xb000, v1
	global_load_dword v66, v1, s[68:69] nt
	v_add_u32_e32 v1, 0xb000, v1
	global_load_dword v67, v1, s[68:69] nt
	v_add_u32_e32 v1, 0xb000, v1
	global_load_dword v68, v1, s[68:69] nt
	v_add_u32_e32 v1, 0xb000, v1
	global_load_dword v69, v1, s[68:69] nt
	v_add_u32_e32 v1, 0xb000, v1
	global_load_dword v70, v1, s[68:69] nt
	v_add_u32_e32 v1, 0xb000, v1
	global_load_dword v71, v1, s[68:69] nt
	v_add_u32_e32 v1, 0xb000, v1
	global_load_dword v72, v1, s[68:69] nt
	v_add_u32_e32 v1, 0xb000, v1
	global_load_dword v73, v1, s[68:69] nt
	v_add_u32_e32 v1, 0xb000, v1
	global_load_dword v74, v1, s[68:69] nt
	v_add_u32_e32 v1, 0xb000, v1
	global_load_dword v75, v1, s[68:69] nt
	v_add_u32_e32 v1, 0xb000, v1
	global_load_dword v76, v1, s[68:69] nt
	v_add_u32_e32 v1, 0xb000, v1
	global_load_dword v77, v1, s[68:69] nt
	v_add_u32_e32 v1, 0xb000, v1
	global_load_dword v78, v1, s[68:69] nt
	v_add_u32_e32 v1, 0xb000, v1
	global_load_dword v79, v1, s[68:69] nt
	v_add_u32_e32 v1, 0xb000, v1
	global_load_dword v80, v1, s[68:69] nt
	v_add_u32_e32 v1, 0xb000, v1
	global_load_dword v81, v1, s[68:69] nt
	v_add_u32_e32 v1, 0xb000, v1
	global_load_dword v82, v1, s[68:69] nt
	v_add_u32_e32 v1, 0xb000, v1
	global_load_dword v83, v1, s[68:69] nt
	v_add_u32_e32 v1, 0xb000, v1
	global_load_dword v84, v1, s[68:69] nt
	v_add_u32_e32 v1, 0xb000, v1
	global_load_dword v85, v1, s[68:69] nt
	v_add_u32_e32 v1, 0xb000, v1
	global_load_dword v86, v1, s[68:69] nt
	v_add_u32_e32 v1, 0xb000, v1
	global_load_dword v87, v1, s[68:69] nt
	v_add_u32_e32 v1, 0xb000, v1
	global_load_dword v88, v1, s[68:69] nt
	v_add_u32_e32 v1, 0xb000, v1
	global_load_dword v89, v1, s[68:69] nt
	v_add_u32_e32 v1, 0xb000, v1
	global_load_dword v90, v1, s[68:69] nt
	v_add_u32_e32 v1, 0xb000, v1
	global_load_dword v91, v1, s[68:69] nt
	v_add_u32_e32 v1, 0xb000, v1
	global_load_dword v92, v1, s[68:69] nt
	v_add_u32_e32 v1, 0xb000, v1
	global_load_dword v93, v1, s[68:69] nt
	v_add_u32_e32 v1, 0xb000, v1
	global_load_dword v94, v1, s[68:69] nt
	v_add_u32_e32 v1, 0xb000, v1
	global_load_dword v95, v1, s[68:69] nt
	s_lshl_b32 s70, s55, 8
	s_add_u32 s70, s60, s70
	s_addc_u32 s71, s61, 0
	global_load_dwordx4 v[104:107], v5, s[70:71]
	global_load_dwordx4 v[108:111], v5, s[70:71] offset:16
	s_waitcnt vmcnt(63)
	s_waitcnt lgkmcnt(0)
	ds_write_b32 v2, v112 offset:0
	ds_write_b32 v2, v113 offset:8
	ds_write_b32 v2, v114 offset:16
	ds_write_b32 v2, v115 offset:24
	ds_write_b32 v2, v116 offset:32
	ds_write_b32 v2, v117 offset:40
	ds_write_b32 v2, v118 offset:48
	ds_write_b32 v2, v119 offset:56
	ds_write_b32 v2, v120 offset:64
	ds_write_b32 v2, v121 offset:72
	ds_write_b32 v2, v122 offset:80
	ds_write_b32 v2, v123 offset:88
	ds_write_b32 v2, v124 offset:96
	ds_write_b32 v2, v125 offset:104
	ds_write_b32 v2, v126 offset:112
	ds_write_b32 v2, v127 offset:120
	ds_write_b32 v2, v128 offset:128
	ds_write_b32 v2, v129 offset:136
	ds_write_b32 v2, v130 offset:144
	ds_write_b32 v2, v131 offset:152
	ds_write_b32 v2, v132 offset:160
	ds_write_b32 v2, v133 offset:168
	ds_write_b32 v2, v134 offset:176
	ds_write_b32 v2, v135 offset:184
	ds_write_b32 v2, v136 offset:192
	ds_write_b32 v2, v137 offset:200
	ds_write_b32 v2, v138 offset:208
	ds_write_b32 v2, v139 offset:216
	ds_write_b32 v2, v140 offset:224
	ds_write_b32 v2, v141 offset:232
	ds_write_b32 v2, v142 offset:240
	ds_write_b32 v2, v143 offset:248
	s_cmp_lt_u32 vcc_lo, 16
	s_cbranch_scc0 .Lmy_cv0_ns
	v_mul_f32_e32 v144, 0x3f4ccccd, v144
	v_mul_f32_e32 v145, 0x3f4ccccd, v145
	v_mul_f32_e32 v146, 0x3f4ccccd, v146
	v_mul_f32_e32 v147, 0x3f4ccccd, v147
	v_mul_f32_e32 v148, 0x3f4ccccd, v148
	v_mul_f32_e32 v149, 0x3f4ccccd, v149
	v_mul_f32_e32 v150, 0x3f4ccccd, v150
	v_mul_f32_e32 v151, 0x3f4ccccd, v151
	s_branch .Lmy_cv0_sd

.Lmy_cv0_sd:
	s_lshl_b32 s70, vcc_hi, 17
	s_lshl_b32 s71, vcc_lo, 7
	s_add_i32 s70, s70, s71
	s_add_u32 s70, s70, 0x1a00000
	s_add_u32 s70, s26, s70
	s_addc_u32 s71, s27, 0
	s_waitcnt lgkmcnt(0)
	ds_read_b64 v[160:161], v3 offset:0
	ds_read_b64 v[162:163], v3 offset:8
	ds_read_b64 v[164:165], v3 offset:16
	ds_read_b64 v[166:167], v3 offset:24
	ds_read_b64 v[168:169], v3 offset:2112
	ds_read_b64 v[170:171], v3 offset:2120
	ds_read_b64 v[172:173], v3 offset:2128
	ds_read_b64 v[174:175], v3 offset:2136
	ds_read_b64 v[176:177], v3 offset:4224
	ds_read_b64 v[178:179], v3 offset:4232
	ds_read_b64 v[180:181], v3 offset:4240
	ds_read_b64 v[182:183], v3 offset:4248
	ds_read_b64 v[184:185], v3 offset:6336
	ds_read_b64 v[186:187], v3 offset:6344
	ds_read_b64 v[188:189], v3 offset:6352
	ds_read_b64 v[190:191], v3 offset:6360
	s_waitcnt lgkmcnt(12)
	v_mul_f32_e32 v160, v160, v144
	v_mul_f32_e32 v161, v161, v145
	v_mul_f32_e32 v162, v162, v146
	v_mul_f32_e32 v163, v163, v147
	v_mul_f32_e32 v164, v164, v148
	v_mul_f32_e32 v165, v165, v149
	v_mul_f32_e32 v166, v166, v150
	v_mul_f32_e32 v167, v167, v151
	v_cvt_pk_bf16_f32 v192, v160, v161
	v_cvt_pk_bf16_f32 v193, v162, v163
	v_cvt_pk_bf16_f32 v194, v164, v165
	v_cvt_pk_bf16_f32 v195, v166, v167
	v_mov_b32_e32 v9, v4
	global_store_dwordx4 v9, v[192:195], s[70:71]
	s_waitcnt lgkmcnt(8)
	v_mul_f32_e32 v168, v168, v144
	v_mul_f32_e32 v169, v169, v145
	v_mul_f32_e32 v170, v170, v146
	v_mul_f32_e32 v171, v171, v147
	v_mul_f32_e32 v172, v172, v148
	v_mul_f32_e32 v173, v173, v149
	v_mul_f32_e32 v174, v174, v150
	v_mul_f32_e32 v175, v175, v151
	v_cvt_pk_bf16_f32 v196, v168, v169
	v_cvt_pk_bf16_f32 v197, v170, v171
	v_cvt_pk_bf16_f32 v198, v172, v173
	v_cvt_pk_bf16_f32 v199, v174, v175
	v_add_u32_e32 v9, 0x8000, v9
	global_store_dwordx4 v9, v[196:199], s[70:71]
	s_waitcnt lgkmcnt(4)
	v_mul_f32_e32 v176, v176, v144
	v_mul_f32_e32 v177, v177, v145
	v_mul_f32_e32 v178, v178, v146
	v_mul_f32_e32 v179, v179, v147
	v_mul_f32_e32 v180, v180, v148
	v_mul_f32_e32 v181, v181, v149
	v_mul_f32_e32 v182, v182, v150
	v_mul_f32_e32 v183, v183, v151
	v_cvt_pk_bf16_f32 v200, v176, v177
	v_cvt_pk_bf16_f32 v201, v178, v179
	v_cvt_pk_bf16_f32 v202, v180, v181
	v_cvt_pk_bf16_f32 v203, v182, v183
	v_add_u32_e32 v9, 0x8000, v9
	global_store_dwordx4 v9, v[200:203], s[70:71]
	s_waitcnt lgkmcnt(0)
	v_mul_f32_e32 v184, v184, v144
	v_mul_f32_e32 v185, v185, v145
	v_mul_f32_e32 v186, v186, v146
	v_mul_f32_e32 v187, v187, v147
	v_mul_f32_e32 v188, v188, v148
	v_mul_f32_e32 v189, v189, v149
	v_mul_f32_e32 v190, v190, v150
	v_mul_f32_e32 v191, v191, v151
	v_cvt_pk_bf16_f32 v204, v184, v185
	v_cvt_pk_bf16_f32 v205, v186, v187
	v_cvt_pk_bf16_f32 v206, v188, v189
	v_cvt_pk_bf16_f32 v207, v190, v191
	v_add_u32_e32 v9, 0x8000, v9
	global_store_dwordx4 v9, v[204:207], s[70:71]
	s_waitcnt vmcnt(34)
	s_waitcnt lgkmcnt(0)
	ds_write_b32 v2, v32 offset:0
	ds_write_b32 v2, v33 offset:8
	ds_write_b32 v2, v34 offset:16
	ds_write_b32 v2, v35 offset:24
	ds_write_b32 v2, v36 offset:32
	ds_write_b32 v2, v37 offset:40
	ds_write_b32 v2, v38 offset:48
	ds_write_b32 v2, v39 offset:56
	ds_write_b32 v2, v40 offset:64
	ds_write_b32 v2, v41 offset:72
	ds_write_b32 v2, v42 offset:80
	ds_write_b32 v2, v43 offset:88
	ds_write_b32 v2, v44 offset:96
	ds_write_b32 v2, v45 offset:104
	ds_write_b32 v2, v46 offset:112
	ds_write_b32 v2, v47 offset:120
	ds_write_b32 v2, v48 offset:128
	ds_write_b32 v2, v49 offset:136
	ds_write_b32 v2, v50 offset:144
	ds_write_b32 v2, v51 offset:152
	ds_write_b32 v2, v52 offset:160
	ds_write_b32 v2, v53 offset:168
	ds_write_b32 v2, v54 offset:176
	ds_write_b32 v2, v55 offset:184
	ds_write_b32 v2, v56 offset:192
	ds_write_b32 v2, v57 offset:200
	ds_write_b32 v2, v58 offset:208
	ds_write_b32 v2, v59 offset:216
	ds_write_b32 v2, v60 offset:224
	ds_write_b32 v2, v61 offset:232
	ds_write_b32 v2, v62 offset:240
	ds_write_b32 v2, v63 offset:248
	s_lshr_b32 s70, s5, 2
	s_lshl_b32 s70, s70, 8
	s_and_b32 s71, s5, 3
	s_lshl_b32 s71, s71, 5
	s_add_i32 s70, s70, s71
	s_add_i32 s70, s70, s54
	s_lshl_b32 s70, s70, 12
	s_lshl_b32 s71, s4, 7
	s_add_i32 s70, s70, s71
	s_add_u32 s70, s70, 0x2200000
	s_add_u32 s70, s26, s70
	s_addc_u32 s71, s27, 0
	s_waitcnt lgkmcnt(0)
	ds_read_b64 v[160:161], v3 offset:0
	ds_read_b64 v[162:163], v3 offset:8
	ds_read_b64 v[164:165], v3 offset:16
	ds_read_b64 v[166:167], v3 offset:24
	ds_read_b64 v[168:169], v3 offset:2112
	ds_read_b64 v[170:171], v3 offset:2120
	ds_read_b64 v[172:173], v3 offset:2128
	ds_read_b64 v[174:175], v3 offset:2136
	ds_read_b64 v[176:177], v3 offset:4224
	ds_read_b64 v[178:179], v3 offset:4232
	ds_read_b64 v[180:181], v3 offset:4240
	ds_read_b64 v[182:183], v3 offset:4248
	ds_read_b64 v[184:185], v3 offset:6336
	ds_read_b64 v[186:187], v3 offset:6344
	ds_read_b64 v[188:189], v3 offset:6352
	ds_read_b64 v[190:191], v3 offset:6360
	s_waitcnt lgkmcnt(12)
	v_mul_f32_e32 v160, v160, v96
	v_mul_f32_e32 v161, v161, v97
	v_mul_f32_e32 v162, v162, v98
	v_mul_f32_e32 v163, v163, v99
	v_mul_f32_e32 v164, v164, v100
	v_mul_f32_e32 v165, v165, v101
	v_mul_f32_e32 v166, v166, v102
	v_mul_f32_e32 v167, v167, v103
	v_cvt_pk_bf16_f32 v192, v160, v161
	v_cvt_pk_bf16_f32 v193, v162, v163
	v_cvt_pk_bf16_f32 v194, v164, v165
	v_cvt_pk_bf16_f32 v195, v166, v167
	v_mov_b32_e32 v9, v4
	global_store_dwordx4 v9, v[192:195], s[70:71]
	s_waitcnt lgkmcnt(8)
	v_mul_f32_e32 v168, v168, v96
	v_mul_f32_e32 v169, v169, v97
	v_mul_f32_e32 v170, v170, v98
	v_mul_f32_e32 v171, v171, v99
	v_mul_f32_e32 v172, v172, v100
	v_mul_f32_e32 v173, v173, v101
	v_mul_f32_e32 v174, v174, v102
	v_mul_f32_e32 v175, v175, v103
	v_cvt_pk_bf16_f32 v196, v168, v169
	v_cvt_pk_bf16_f32 v197, v170, v171
	v_cvt_pk_bf16_f32 v198, v172, v173
	v_cvt_pk_bf16_f32 v199, v174, v175
	v_add_u32_e32 v9, 0x8000, v9
	global_store_dwordx4 v9, v[196:199], s[70:71]
	s_waitcnt lgkmcnt(4)
	v_mul_f32_e32 v176, v176, v96
	v_mul_f32_e32 v177, v177, v97
	v_mul_f32_e32 v178, v178, v98
	v_mul_f32_e32 v179, v179, v99
	v_mul_f32_e32 v180, v180, v100
	v_mul_f32_e32 v181, v181, v101
	v_mul_f32_e32 v182, v182, v102
	v_mul_f32_e32 v183, v183, v103
	v_cvt_pk_bf16_f32 v200, v176, v177
	v_cvt_pk_bf16_f32 v201, v178, v179
	v_cvt_pk_bf16_f32 v202, v180, v181
	v_cvt_pk_bf16_f32 v203, v182, v183
	v_add_u32_e32 v9, 0x8000, v9
	global_store_dwordx4 v9, v[200:203], s[70:71]
	s_waitcnt lgkmcnt(0)
	v_mul_f32_e32 v184, v184, v96
	v_mul_f32_e32 v185, v185, v97
	v_mul_f32_e32 v186, v186, v98
	v_mul_f32_e32 v187, v187, v99
	v_mul_f32_e32 v188, v188, v100
	v_mul_f32_e32 v189, v189, v101
	v_mul_f32_e32 v190, v190, v102
	v_mul_f32_e32 v191, v191, v103
	v_cvt_pk_bf16_f32 v204, v184, v185
	v_cvt_pk_bf16_f32 v205, v186, v187
	v_cvt_pk_bf16_f32 v206, v188, v189
	v_cvt_pk_bf16_f32 v207, v190, v191
	v_add_u32_e32 v9, 0x8000, v9
	global_store_dwordx4 v9, v[204:207], s[70:71]
	s_waitcnt vmcnt(0)
	s_waitcnt lgkmcnt(0)
	ds_write_b32 v2, v64 offset:0
	ds_write_b32 v2, v65 offset:8
	ds_write_b32 v2, v66 offset:16
	ds_write_b32 v2, v67 offset:24
	ds_write_b32 v2, v68 offset:32
	ds_write_b32 v2, v69 offset:40
	ds_write_b32 v2, v70 offset:48
	ds_write_b32 v2, v71 offset:56
	ds_write_b32 v2, v72 offset:64
	ds_write_b32 v2, v73 offset:72
	ds_write_b32 v2, v74 offset:80
	ds_write_b32 v2, v75 offset:88
	ds_write_b32 v2, v76 offset:96
	ds_write_b32 v2, v77 offset:104
	ds_write_b32 v2, v78 offset:112
	ds_write_b32 v2, v79 offset:120
	ds_write_b32 v2, v80 offset:128
	ds_write_b32 v2, v81 offset:136
	ds_write_b32 v2, v82 offset:144
	ds_write_b32 v2, v83 offset:152
	ds_write_b32 v2, v84 offset:160
	ds_write_b32 v2, v85 offset:168
	ds_write_b32 v2, v86 offset:176
	ds_write_b32 v2, v87 offset:184
	ds_write_b32 v2, v88 offset:192
	ds_write_b32 v2, v89 offset:200
	ds_write_b32 v2, v90 offset:208
	ds_write_b32 v2, v91 offset:216
	ds_write_b32 v2, v92 offset:224
	ds_write_b32 v2, v93 offset:232
	ds_write_b32 v2, v94 offset:240
	ds_write_b32 v2, v95 offset:248
	s_lshr_b32 s70, s67, 2
	s_lshl_b32 s70, s70, 8
	s_and_b32 s71, s67, 3
	s_lshl_b32 s71, s71, 5
	s_add_i32 s70, s70, s71
	s_add_i32 s70, s70, s40
	s_lshl_b32 s70, s70, 12
	s_lshl_b32 s71, s55, 7
	s_add_i32 s70, s70, s71
	s_add_u32 s70, s70, 0x2200000
	s_add_u32 s70, s26, s70
	s_addc_u32 s71, s27, 0
	s_waitcnt lgkmcnt(0)
	ds_read_b64 v[160:161], v3 offset:0
	ds_read_b64 v[162:163], v3 offset:8
	ds_read_b64 v[164:165], v3 offset:16
	ds_read_b64 v[166:167], v3 offset:24
	ds_read_b64 v[168:169], v3 offset:2112
	ds_read_b64 v[170:171], v3 offset:2120
	ds_read_b64 v[172:173], v3 offset:2128
	ds_read_b64 v[174:175], v3 offset:2136
	ds_read_b64 v[176:177], v3 offset:4224
	ds_read_b64 v[178:179], v3 offset:4232
	ds_read_b64 v[180:181], v3 offset:4240
	ds_read_b64 v[182:183], v3 offset:4248
	ds_read_b64 v[184:185], v3 offset:6336
	ds_read_b64 v[186:187], v3 offset:6344
	ds_read_b64 v[188:189], v3 offset:6352
	ds_read_b64 v[190:191], v3 offset:6360
	s_waitcnt lgkmcnt(12)
	v_mul_f32_e32 v160, v160, v104
	v_mul_f32_e32 v161, v161, v105
	v_mul_f32_e32 v162, v162, v106
	v_mul_f32_e32 v163, v163, v107
	v_mul_f32_e32 v164, v164, v108
	v_mul_f32_e32 v165, v165, v109
	v_mul_f32_e32 v166, v166, v110
	v_mul_f32_e32 v167, v167, v111
	v_cvt_pk_bf16_f32 v192, v160, v161
	v_cvt_pk_bf16_f32 v193, v162, v163
	v_cvt_pk_bf16_f32 v194, v164, v165
	v_cvt_pk_bf16_f32 v195, v166, v167
	v_mov_b32_e32 v9, v4
	global_store_dwordx4 v9, v[192:195], s[70:71]
	s_waitcnt lgkmcnt(8)
	v_mul_f32_e32 v168, v168, v104
	v_mul_f32_e32 v169, v169, v105
	v_mul_f32_e32 v170, v170, v106
	v_mul_f32_e32 v171, v171, v107
	v_mul_f32_e32 v172, v172, v108
	v_mul_f32_e32 v173, v173, v109
	v_mul_f32_e32 v174, v174, v110
	v_mul_f32_e32 v175, v175, v111
	v_cvt_pk_bf16_f32 v196, v168, v169
	v_cvt_pk_bf16_f32 v197, v170, v171
	v_cvt_pk_bf16_f32 v198, v172, v173
	v_cvt_pk_bf16_f32 v199, v174, v175
	v_add_u32_e32 v9, 0x8000, v9
	global_store_dwordx4 v9, v[196:199], s[70:71]
	s_waitcnt lgkmcnt(4)
	v_mul_f32_e32 v176, v176, v104
	v_mul_f32_e32 v177, v177, v105
	v_mul_f32_e32 v178, v178, v106
	v_mul_f32_e32 v179, v179, v107
	v_mul_f32_e32 v180, v180, v108
	v_mul_f32_e32 v181, v181, v109
	v_mul_f32_e32 v182, v182, v110
	v_mul_f32_e32 v183, v183, v111
	v_cvt_pk_bf16_f32 v200, v176, v177
	v_cvt_pk_bf16_f32 v201, v178, v179
	v_cvt_pk_bf16_f32 v202, v180, v181
	v_cvt_pk_bf16_f32 v203, v182, v183
	v_add_u32_e32 v9, 0x8000, v9
	global_store_dwordx4 v9, v[200:203], s[70:71]
	s_waitcnt lgkmcnt(0)
	v_mul_f32_e32 v184, v184, v104
	v_mul_f32_e32 v185, v185, v105
	v_mul_f32_e32 v186, v186, v106
	v_mul_f32_e32 v187, v187, v107
	v_mul_f32_e32 v188, v188, v108
	v_mul_f32_e32 v189, v189, v109
	v_mul_f32_e32 v190, v190, v110
	v_mul_f32_e32 v191, v191, v111
	v_cvt_pk_bf16_f32 v204, v184, v185
	v_cvt_pk_bf16_f32 v205, v186, v187
	v_cvt_pk_bf16_f32 v206, v188, v189
	v_cvt_pk_bf16_f32 v207, v190, v191
	v_add_u32_e32 v9, 0x8000, v9
	global_store_dwordx4 v9, v[204:207], s[70:71]
	s_waitcnt vmcnt(0) lgkmcnt(0)

.LBB0_340:
	s_cmp_gt_u32 s29, 2
	s_cselect_b64 s[0:1], -1, 0
	s_and_b64 s[0:1], s[20:21], s[0:1]
	s_andn2_b64 vcc, exec, s[0:1]
	s_cbranch_vccnz .LBB0_392
	s_waitcnt vmcnt(0)
	v_cmp_eq_u32_e32 vcc, 0, v208
	s_waitcnt vmcnt(0) lgkmcnt(0)
	s_barrier
	v_readfirstlane_b32 s3, v208
	s_nop 3
	s_lshr_b32 s3, s3, 6
	s_cmp_eq_u32 s3, 0
	s_cbranch_scc1 .Lmy_cv1_end
	v_readlane_b32 s36, v237, 0
	v_readlane_b32 s37, v237, 1
	s_mul_i32 s4, s2, 7
	s_add_i32 s4, s4, s3
	s_add_i32 s4, s4, -1
	s_lshl_b32 s72, s3, 14
	s_mov_b32 s3, s4
	s_nop 4
	s_load_dwordx4 s[60:63], s[36:37], 0x60
	s_load_dwordx2 s[64:65], s[36:37], 0x70
	v_lshrrev_b32_e32 v6, 5, v209
	v_and_b32_e32 v7, 31, v209
	v_mul_u32_u24_e32 v0, 0x1600, v6
	v_add_lshl_u32 v0, v0, v7, 2
	v_lshlrev_b32_e32 v152, 11, v6
	v_add_lshl_u32 v152, v152, v7, 2
	v_mul_u32_u24_e32 v2, 66, v7
	v_add_lshl_u32 v2, v2, v6, 2
	v_add_u32_e32 v2, s72, v2
	v_and_b32_e32 v8, 7, v209
	v_lshrrev_b32_e32 v9, 3, v209
	v_mul_u32_u24_e32 v3, 0x108, v9
	v_lshl_add_u32 v3, v8, 5, v3
	v_add_u32_e32 v3, s72, v3
	v_lshlrev_b32_e32 v4, 12, v9
	v_lshl_add_u32 v4, v8, 4, v4
	v_lshlrev_b32_e32 v5, 5, v8
	s_waitcnt lgkmcnt(0)
	s_cmpk_lt_u32 s3, 0x200
	s_cbranch_scc0 .Lmy_cv1_no3a
	s_mov_b32 s66, s3
	s_cmpk_ge_u32 s66, 0x1600
	s_cselect_b32 s68, s64, s62
	s_cselect_b32 s69, s65, s63
	s_cselect_b32 s41, 0x1600, 0
	s_sub_u32 s41, s66, s41
	s_mul_hi_u32 vcc_lo, s41, 0xba2e8ba3
	s_lshr_b32 vcc_lo, vcc_lo, 7
	s_mul_i32 s70, vcc_lo, 0xb0
	s_sub_u32 vcc_hi, s41, s70
	s_mul_i32 s70, vcc_lo, 0x160000
	s_lshl_b32 s71, vcc_hi, 7
	s_add_u32 s68, s68, s70
	s_addc_u32 s69, s69, 0
	s_add_u32 s68, s68, s71
	s_addc_u32 s69, s69, 0
	v_mov_b32_e32 v1, v0
	global_load_dword v112, v1, s[68:69] nt
	v_add_u32_e32 v1, 0xb000, v1
	global_load_dword v113, v1, s[68:69] nt
	v_add_u32_e32 v1, 0xb000, v1
	global_load_dword v114, v1, s[68:69] nt
	v_add_u32_e32 v1, 0xb000, v1
	global_load_dword v115, v1, s[68:69] nt
	v_add_u32_e32 v1, 0xb000, v1
	global_load_dword v116, v1, s[68:69] nt
	v_add_u32_e32 v1, 0xb000, v1
	global_load_dword v117, v1, s[68:69] nt
	v_add_u32_e32 v1, 0xb000, v1
	global_load_dword v118, v1, s[68:69] nt
	v_add_u32_e32 v1, 0xb000, v1
	global_load_dword v119, v1, s[68:69] nt
	v_add_u32_e32 v1, 0xb000, v1
	global_load_dword v120, v1, s[68:69] nt
	v_add_u32_e32 v1, 0xb000, v1
	global_load_dword v121, v1, s[68:69] nt
	v_add_u32_e32 v1, 0xb000, v1
	global_load_dword v122, v1, s[68:69] nt
	v_add_u32_e32 v1, 0xb000, v1
	global_load_dword v123, v1, s[68:69] nt
	v_add_u32_e32 v1, 0xb000, v1
	global_load_dword v124, v1, s[68:69] nt
	v_add_u32_e32 v1, 0xb000, v1
	global_load_dword v125, v1, s[68:69] nt
	v_add_u32_e32 v1, 0xb000, v1
	global_load_dword v126, v1, s[68:69] nt
	v_add_u32_e32 v1, 0xb000, v1
	global_load_dword v127, v1, s[68:69] nt
	v_add_u32_e32 v1, 0xb000, v1
	global_load_dword v128, v1, s[68:69] nt
	v_add_u32_e32 v1, 0xb000, v1
	global_load_dword v129, v1, s[68:69] nt
	v_add_u32_e32 v1, 0xb000, v1
	global_load_dword v130, v1, s[68:69] nt
	v_add_u32_e32 v1, 0xb000, v1
	global_load_dword v131, v1, s[68:69] nt
	v_add_u32_e32 v1, 0xb000, v1
	global_load_dword v132, v1, s[68:69] nt
	v_add_u32_e32 v1, 0xb000, v1
	global_load_dword v133, v1, s[68:69] nt
	v_add_u32_e32 v1, 0xb000, v1
	global_load_dword v134, v1, s[68:69] nt
	v_add_u32_e32 v1, 0xb000, v1
	global_load_dword v135, v1, s[68:69] nt
	v_add_u32_e32 v1, 0xb000, v1
	global_load_dword v136, v1, s[68:69] nt
	v_add_u32_e32 v1, 0xb000, v1
	global_load_dword v137, v1, s[68:69] nt
	v_add_u32_e32 v1, 0xb000, v1
	global_load_dword v138, v1, s[68:69] nt
	v_add_u32_e32 v1, 0xb000, v1
	global_load_dword v139, v1, s[68:69] nt
	v_add_u32_e32 v1, 0xb000, v1
	global_load_dword v140, v1, s[68:69] nt
	v_add_u32_e32 v1, 0xb000, v1
	global_load_dword v141, v1, s[68:69] nt
	v_add_u32_e32 v1, 0xb000, v1
	global_load_dword v142, v1, s[68:69] nt
	v_add_u32_e32 v1, 0xb000, v1
	global_load_dword v143, v1, s[68:69] nt
	s_lshl_b32 s70, vcc_lo, 8
	s_add_u32 s70, s60, s70
	s_addc_u32 s71, s61, 0
	global_load_dwordx4 v[144:147], v5, s[70:71]
	global_load_dwordx4 v[148:151], v5, s[70:71] offset:16
.Lmy_cv1_no3a:
	s_add_i32 s66, s3, 4096
	s_cmpk_ge_u32 s66, 0x1600
	s_cselect_b32 s68, s64, s62
	s_cselect_b32 s69, s65, s63
	s_cselect_b32 s54, 128, 0
	s_cselect_b32 s41, 0x1600, 0
	s_sub_u32 s41, s66, s41
	s_mul_hi_u32 s4, s41, 0xba2e8ba3
	s_lshr_b32 s4, s4, 7
	s_mul_i32 s70, s4, 0xb0
	s_sub_u32 s5, s41, s70
	s_mul_i32 s70, s4, 0x160000
	s_lshl_b32 s71, s5, 7
	s_add_u32 s68, s68, s70
	s_addc_u32 s69, s69, 0
	s_add_u32 s68, s68, s71
	s_addc_u32 s69, s69, 0
	v_mov_b32_e32 v1, v0
	global_load_dword v32, v1, s[68:69] nt
	v_add_u32_e32 v1, 0xb000, v1
	global_load_dword v33, v1, s[68:69] nt
	v_add_u32_e32 v1, 0xb000, v1
	global_load_dword v34, v1, s[68:69] nt
	v_add_u32_e32 v1, 0xb000, v1
	global_load_dword v35, v1, s[68:69] nt
	v_add_u32_e32 v1, 0xb000, v1
	global_load_dword v36, v1, s[68:69] nt
	v_add_u32_e32 v1, 0xb000, v1
	global_load_dword v37, v1, s[68:69] nt
	v_add_u32_e32 v1, 0xb000, v1
	global_load_dword v38, v1, s[68:69] nt
	v_add_u32_e32 v1, 0xb000, v1
	global_load_dword v39, v1, s[68:69] nt
	v_add_u32_e32 v1, 0xb000, v1
	global_load_dword v40, v1, s[68:69] nt
	v_add_u32_e32 v1, 0xb000, v1
	global_load_dword v41, v1, s[68:69] nt
	v_add_u32_e32 v1, 0xb000, v1
	global_load_dword v42, v1, s[68:69] nt
	v_add_u32_e32 v1, 0xb000, v1
	global_load_dword v43, v1, s[68:69] nt
	v_add_u32_e32 v1, 0xb000, v1
	global_load_dword v44, v1, s[68:69] nt
	v_add_u32_e32 v1, 0xb000, v1
	global_load_dword v45, v1, s[68:69] nt
	v_add_u32_e32 v1, 0xb000, v1
	global_load_dword v46, v1, s[68:69] nt
	v_add_u32_e32 v1, 0xb000, v1
	global_load_dword v47, v1, s[68:69] nt
	v_add_u32_e32 v1, 0xb000, v1
	global_load_dword v48, v1, s[68:69] nt
	v_add_u32_e32 v1, 0xb000, v1
	global_load_dword v49, v1, s[68:69] nt
	v_add_u32_e32 v1, 0xb000, v1
	global_load_dword v50, v1, s[68:69] nt
	v_add_u32_e32 v1, 0xb000, v1
	global_load_dword v51, v1, s[68:69] nt
	v_add_u32_e32 v1, 0xb000, v1
	global_load_dword v52, v1, s[68:69] nt
	v_add_u32_e32 v1, 0xb000, v1
	global_load_dword v53, v1, s[68:69] nt
	v_add_u32_e32 v1, 0xb000, v1
	global_load_dword v54, v1, s[68:69] nt
	v_add_u32_e32 v1, 0xb000, v1
	global_load_dword v55, v1, s[68:69] nt
	v_add_u32_e32 v1, 0xb000, v1
	global_load_dword v56, v1, s[68:69] nt
	v_add_u32_e32 v1, 0xb000, v1
	global_load_dword v57, v1, s[68:69] nt
	v_add_u32_e32 v1, 0xb000, v1
	global_load_dword v58, v1, s[68:69] nt
	v_add_u32_e32 v1, 0xb000, v1
	global_load_dword v59, v1, s[68:69] nt
	v_add_u32_e32 v1, 0xb000, v1
	global_load_dword v60, v1, s[68:69] nt
	v_add_u32_e32 v1, 0xb000, v1
	global_load_dword v61, v1, s[68:69] nt
	v_add_u32_e32 v1, 0xb000, v1
	global_load_dword v62, v1, s[68:69] nt
	v_add_u32_e32 v1, 0xb000, v1
	global_load_dword v63, v1, s[68:69] nt
	s_lshl_b32 s70, s4, 8
	s_add_u32 s70, s60, s70
	s_addc_u32 s71, s61, 0
	global_load_dwordx4 v[96:99], v5, s[70:71]
	global_load_dwordx4 v[100:103], v5, s[70:71] offset:16
	s_addk_i32 s66, 0x700
	s_cmpk_ge_u32 s66, 0x1600
	s_cselect_b32 s68, s64, s62
	s_cselect_b32 s69, s65, s63
	s_cselect_b32 s40, 128, 0
	s_cselect_b32 s41, 0x1600, 0
	s_sub_u32 s41, s66, s41
	s_mul_hi_u32 s55, s41, 0xba2e8ba3
	s_lshr_b32 s55, s55, 7
	s_mul_i32 s70, s55, 0xb0
	s_sub_u32 s67, s41, s70
	s_mul_i32 s70, s55, 0x160000
	s_lshl_b32 s71, s67, 7
	s_add_u32 s68, s68, s70
	s_addc_u32 s69, s69, 0
	s_add_u32 s68, s68, s71
	s_addc_u32 s69, s69, 0
	v_mov_b32_e32 v1, v0
	global_load_dword v64, v1, s[68:69] nt
	v_add_u32_e32 v1, 0xb000, v1
	global_load_dword v65, v1, s[68:69] nt
	v_add_u32_e32 v1, 0xb000, v1
	global_load_dword v66, v1, s[68:69] nt
	v_add_u32_e32 v1, 0xb000, v1
	global_load_dword v67, v1, s[68:69] nt
	v_add_u32_e32 v1, 0xb000, v1
	global_load_dword v68, v1, s[68:69] nt
	v_add_u32_e32 v1, 0xb000, v1
	global_load_dword v69, v1, s[68:69] nt
	v_add_u32_e32 v1, 0xb000, v1
	global_load_dword v70, v1, s[68:69] nt
	v_add_u32_e32 v1, 0xb000, v1
	global_load_dword v71, v1, s[68:69] nt
	v_add_u32_e32 v1, 0xb000, v1
	global_load_dword v72, v1, s[68:69] nt
	v_add_u32_e32 v1, 0xb000, v1
	global_load_dword v73, v1, s[68:69] nt
	v_add_u32_e32 v1, 0xb000, v1
	global_load_dword v74, v1, s[68:69] nt
	v_add_u32_e32 v1, 0xb000, v1
	global_load_dword v75, v1, s[68:69] nt
	v_add_u32_e32 v1, 0xb000, v1
	global_load_dword v76, v1, s[68:69] nt
	v_add_u32_e32 v1, 0xb000, v1
	global_load_dword v77, v1, s[68:69] nt
	v_add_u32_e32 v1, 0xb000, v1
	global_load_dword v78, v1, s[68:69] nt
	v_add_u32_e32 v1, 0xb000, v1
	global_load_dword v79, v1, s[68:69] nt
	v_add_u32_e32 v1, 0xb000, v1
	global_load_dword v80, v1, s[68:69] nt
	v_add_u32_e32 v1, 0xb000, v1
	global_load_dword v81, v1, s[68:69] nt
	v_add_u32_e32 v1, 0xb000, v1
	global_load_dword v82, v1, s[68:69] nt
	v_add_u32_e32 v1, 0xb000, v1
	global_load_dword v83, v1, s[68:69] nt
	v_add_u32_e32 v1, 0xb000, v1
	global_load_dword v84, v1, s[68:69] nt
	v_add_u32_e32 v1, 0xb000, v1
	global_load_dword v85, v1, s[68:69] nt
	v_add_u32_e32 v1, 0xb000, v1
	global_load_dword v86, v1, s[68:69] nt
	v_add_u32_e32 v1, 0xb000, v1
	global_load_dword v87, v1, s[68:69] nt
	v_add_u32_e32 v1, 0xb000, v1
	global_load_dword v88, v1, s[68:69] nt
	v_add_u32_e32 v1, 0xb000, v1
	global_load_dword v89, v1, s[68:69] nt
	v_add_u32_e32 v1, 0xb000, v1
	global_load_dword v90, v1, s[68:69] nt
	v_add_u32_e32 v1, 0xb000, v1
	global_load_dword v91, v1, s[68:69] nt
	v_add_u32_e32 v1, 0xb000, v1
	global_load_dword v92, v1, s[68:69] nt
	v_add_u32_e32 v1, 0xb000, v1
	global_load_dword v93, v1, s[68:69] nt
	v_add_u32_e32 v1, 0xb000, v1
	global_load_dword v94, v1, s[68:69] nt
	v_add_u32_e32 v1, 0xb000, v1
	global_load_dword v95, v1, s[68:69] nt
	s_lshl_b32 s70, s55, 8
	s_add_u32 s70, s60, s70
	s_addc_u32 s71, s61, 0
	global_load_dwordx4 v[104:107], v5, s[70:71]
	global_load_dwordx4 v[108:111], v5, s[70:71] offset:16
	s_cmpk_lt_u32 s3, 0x200
	s_cbranch_scc0 .Lmy_cv1_no3b
	s_waitcnt vmcnt(63)
	s_waitcnt lgkmcnt(0)
	ds_write_b32 v2, v112 offset:0
	ds_write_b32 v2, v113 offset:8
	ds_write_b32 v2, v114 offset:16
	ds_write_b32 v2, v115 offset:24
	ds_write_b32 v2, v116 offset:32
	ds_write_b32 v2, v117 offset:40
	ds_write_b32 v2, v118 offset:48
	ds_write_b32 v2, v119 offset:56
	ds_write_b32 v2, v120 offset:64
	ds_write_b32 v2, v121 offset:72
	ds_write_b32 v2, v122 offset:80
	ds_write_b32 v2, v123 offset:88
	ds_write_b32 v2, v124 offset:96
	ds_write_b32 v2, v125 offset:104
	ds_write_b32 v2, v126 offset:112
	ds_write_b32 v2, v127 offset:120
	ds_write_b32 v2, v128 offset:128
	ds_write_b32 v2, v129 offset:136
	ds_write_b32 v2, v130 offset:144
	ds_write_b32 v2, v131 offset:152
	ds_write_b32 v2, v132 offset:160
	ds_write_b32 v2, v133 offset:168
	ds_write_b32 v2, v134 offset:176
	ds_write_b32 v2, v135 offset:184
	ds_write_b32 v2, v136 offset:192
	ds_write_b32 v2, v137 offset:200
	ds_write_b32 v2, v138 offset:208
	ds_write_b32 v2, v139 offset:216
	ds_write_b32 v2, v140 offset:224
	ds_write_b32 v2, v141 offset:232
	ds_write_b32 v2, v142 offset:240
	ds_write_b32 v2, v143 offset:248
	s_lshr_b32 s70, vcc_hi, 2
	s_lshl_b32 s70, s70, 8
	s_and_b32 s71, vcc_hi, 3
	s_lshl_b32 s71, s71, 5
	s_add_i32 s70, s70, s71
	s_lshl_b32 s70, s70, 12
	s_lshl_b32 s71, vcc_lo, 7
	s_add_i32 s70, s70, s71
	s_add_u32 s70, s70, 0x2200000
	s_add_u32 s70, s26, s70
	s_addc_u32 s71, s27, 0
	s_waitcnt lgkmcnt(0)
	ds_read_b64 v[160:161], v3 offset:0
	ds_read_b64 v[162:163], v3 offset:8
	ds_read_b64 v[164:165], v3 offset:16
	ds_read_b64 v[166:167], v3 offset:24
	ds_read_b64 v[168:169], v3 offset:2112
	ds_read_b64 v[170:171], v3 offset:2120
	ds_read_b64 v[172:173], v3 offset:2128
	ds_read_b64 v[174:175], v3 offset:2136
	ds_read_b64 v[176:177], v3 offset:4224
	ds_read_b64 v[178:179], v3 offset:4232
	ds_read_b64 v[180:181], v3 offset:4240
	ds_read_b64 v[182:183], v3 offset:4248
	ds_read_b64 v[184:185], v3 offset:6336
	ds_read_b64 v[186:187], v3 offset:6344
	ds_read_b64 v[188:189], v3 offset:6352
	ds_read_b64 v[190:191], v3 offset:6360
	s_waitcnt lgkmcnt(12)
	v_mul_f32_e32 v160, v160, v144
	v_mul_f32_e32 v161, v161, v145
	v_mul_f32_e32 v162, v162, v146
	v_mul_f32_e32 v163, v163, v147
	v_mul_f32_e32 v164, v164, v148
	v_mul_f32_e32 v165, v165, v149
	v_mul_f32_e32 v166, v166, v150
	v_mul_f32_e32 v167, v167, v151
	v_cvt_pk_bf16_f32 v192, v160, v161
	v_cvt_pk_bf16_f32 v193, v162, v163
	v_cvt_pk_bf16_f32 v194, v164, v165
	v_cvt_pk_bf16_f32 v195, v166, v167
	v_mov_b32_e32 v9, v4
	global_store_dwordx4 v9, v[192:195], s[70:71]
	s_waitcnt lgkmcnt(8)
	v_mul_f32_e32 v168, v168, v144
	v_mul_f32_e32 v169, v169, v145
	v_mul_f32_e32 v170, v170, v146
	v_mul_f32_e32 v171, v171, v147
	v_mul_f32_e32 v172, v172, v148
	v_mul_f32_e32 v173, v173, v149
	v_mul_f32_e32 v174, v174, v150
	v_mul_f32_e32 v175, v175, v151
	v_cvt_pk_bf16_f32 v196, v168, v169
	v_cvt_pk_bf16_f32 v197, v170, v171
	v_cvt_pk_bf16_f32 v198, v172, v173
	v_cvt_pk_bf16_f32 v199, v174, v175
	v_add_u32_e32 v9, 0x8000, v9
	global_store_dwordx4 v9, v[196:199], s[70:71]
	s_waitcnt lgkmcnt(4)
	v_mul_f32_e32 v176, v176, v144
	v_mul_f32_e32 v177, v177, v145
	v_mul_f32_e32 v178, v178, v146
	v_mul_f32_e32 v179, v179, v147
	v_mul_f32_e32 v180, v180, v148
	v_mul_f32_e32 v181, v181, v149
	v_mul_f32_e32 v182, v182, v150
	v_mul_f32_e32 v183, v183, v151
	v_cvt_pk_bf16_f32 v200, v176, v177
	v_cvt_pk_bf16_f32 v201, v178, v179
	v_cvt_pk_bf16_f32 v202, v180, v181
	v_cvt_pk_bf16_f32 v203, v182, v183
	v_add_u32_e32 v9, 0x8000, v9
	global_store_dwordx4 v9, v[200:203], s[70:71]
	s_waitcnt lgkmcnt(0)
	v_mul_f32_e32 v184, v184, v144
	v_mul_f32_e32 v185, v185, v145
	v_mul_f32_e32 v186, v186, v146
	v_mul_f32_e32 v187, v187, v147
	v_mul_f32_e32 v188, v188, v148
	v_mul_f32_e32 v189, v189, v149
	v_mul_f32_e32 v190, v190, v150
	v_mul_f32_e32 v191, v191, v151
	v_cvt_pk_bf16_f32 v204, v184, v185
	v_cvt_pk_bf16_f32 v205, v186, v187
	v_cvt_pk_bf16_f32 v206, v188, v189
	v_cvt_pk_bf16_f32 v207, v190, v191
	v_add_u32_e32 v9, 0x8000, v9
	global_store_dwordx4 v9, v[204:207], s[70:71]
.Lmy_cv1_no3b:
	s_waitcnt vmcnt(34)
	s_waitcnt lgkmcnt(0)
	ds_write_b32 v2, v32 offset:0
	ds_write_b32 v2, v33 offset:8
	ds_write_b32 v2, v34 offset:16
	ds_write_b32 v2, v35 offset:24
	ds_write_b32 v2, v36 offset:32
	ds_write_b32 v2, v37 offset:40
	ds_write_b32 v2, v38 offset:48
	ds_write_b32 v2, v39 offset:56
	ds_write_b32 v2, v40 offset:64
	ds_write_b32 v2, v41 offset:72
	ds_write_b32 v2, v42 offset:80
	ds_write_b32 v2, v43 offset:88
	ds_write_b32 v2, v44 offset:96
	ds_write_b32 v2, v45 offset:104
	ds_write_b32 v2, v46 offset:112
	ds_write_b32 v2, v47 offset:120
	ds_write_b32 v2, v48 offset:128
	ds_write_b32 v2, v49 offset:136
	ds_write_b32 v2, v50 offset:144
	ds_write_b32 v2, v51 offset:152
	ds_write_b32 v2, v52 offset:160
	ds_write_b32 v2, v53 offset:168
	ds_write_b32 v2, v54 offset:176
	ds_write_b32 v2, v55 offset:184
	ds_write_b32 v2, v56 offset:192
	ds_write_b32 v2, v57 offset:200
	ds_write_b32 v2, v58 offset:208
	ds_write_b32 v2, v59 offset:216
	ds_write_b32 v2, v60 offset:224
	ds_write_b32 v2, v61 offset:232
	ds_write_b32 v2, v62 offset:240
	ds_write_b32 v2, v63 offset:248
	s_lshr_b32 s70, s5, 2
	s_lshl_b32 s70, s70, 8
	s_and_b32 s71, s5, 3
	s_lshl_b32 s71, s71, 5
	s_add_i32 s70, s70, s71
	s_add_i32 s70, s70, s54
	s_lshl_b32 s70, s70, 12
	s_lshl_b32 s71, s4, 7
	s_add_i32 s70, s70, s71
	s_add_u32 s70, s70, 0x2200000
	s_add_u32 s70, s26, s70
	s_addc_u32 s71, s27, 0
	s_waitcnt lgkmcnt(0)
	ds_read_b64 v[160:161], v3 offset:0
	ds_read_b64 v[162:163], v3 offset:8
	ds_read_b64 v[164:165], v3 offset:16
	ds_read_b64 v[166:167], v3 offset:24
	ds_read_b64 v[168:169], v3 offset:2112
	ds_read_b64 v[170:171], v3 offset:2120
	ds_read_b64 v[172:173], v3 offset:2128
	ds_read_b64 v[174:175], v3 offset:2136
	ds_read_b64 v[176:177], v3 offset:4224
	ds_read_b64 v[178:179], v3 offset:4232
	ds_read_b64 v[180:181], v3 offset:4240
	ds_read_b64 v[182:183], v3 offset:4248
	ds_read_b64 v[184:185], v3 offset:6336
	ds_read_b64 v[186:187], v3 offset:6344
	ds_read_b64 v[188:189], v3 offset:6352
	ds_read_b64 v[190:191], v3 offset:6360
	s_waitcnt lgkmcnt(12)
	v_mul_f32_e32 v160, v160, v96
	v_mul_f32_e32 v161, v161, v97
	v_mul_f32_e32 v162, v162, v98
	v_mul_f32_e32 v163, v163, v99
	v_mul_f32_e32 v164, v164, v100
	v_mul_f32_e32 v165, v165, v101
	v_mul_f32_e32 v166, v166, v102
	v_mul_f32_e32 v167, v167, v103
	v_cvt_pk_bf16_f32 v192, v160, v161
	v_cvt_pk_bf16_f32 v193, v162, v163
	v_cvt_pk_bf16_f32 v194, v164, v165
	v_cvt_pk_bf16_f32 v195, v166, v167
	v_mov_b32_e32 v9, v4
	global_store_dwordx4 v9, v[192:195], s[70:71]
	s_waitcnt lgkmcnt(8)
	v_mul_f32_e32 v168, v168, v96
	v_mul_f32_e32 v169, v169, v97
	v_mul_f32_e32 v170, v170, v98
	v_mul_f32_e32 v171, v171, v99
	v_mul_f32_e32 v172, v172, v100
	v_mul_f32_e32 v173, v173, v101
	v_mul_f32_e32 v174, v174, v102
	v_mul_f32_e32 v175, v175, v103
	v_cvt_pk_bf16_f32 v196, v168, v169
	v_cvt_pk_bf16_f32 v197, v170, v171
	v_cvt_pk_bf16_f32 v198, v172, v173
	v_cvt_pk_bf16_f32 v199, v174, v175
	v_add_u32_e32 v9, 0x8000, v9
	global_store_dwordx4 v9, v[196:199], s[70:71]
	s_waitcnt lgkmcnt(4)
	v_mul_f32_e32 v176, v176, v96
	v_mul_f32_e32 v177, v177, v97
	v_mul_f32_e32 v178, v178, v98
	v_mul_f32_e32 v179, v179, v99
	v_mul_f32_e32 v180, v180, v100
	v_mul_f32_e32 v181, v181, v101
	v_mul_f32_e32 v182, v182, v102
	v_mul_f32_e32 v183, v183, v103
	v_cvt_pk_bf16_f32 v200, v176, v177
	v_cvt_pk_bf16_f32 v201, v178, v179
	v_cvt_pk_bf16_f32 v202, v180, v181
	v_cvt_pk_bf16_f32 v203, v182, v183
	v_add_u32_e32 v9, 0x8000, v9
	global_store_dwordx4 v9, v[200:203], s[70:71]
	s_waitcnt lgkmcnt(0)
	v_mul_f32_e32 v184, v184, v96
	v_mul_f32_e32 v185, v185, v97
	v_mul_f32_e32 v186, v186, v98
	v_mul_f32_e32 v187, v187, v99
	v_mul_f32_e32 v188, v188, v100
	v_mul_f32_e32 v189, v189, v101
	v_mul_f32_e32 v190, v190, v102
	v_mul_f32_e32 v191, v191, v103
	v_cvt_pk_bf16_f32 v204, v184, v185
	v_cvt_pk_bf16_f32 v205, v186, v187
	v_cvt_pk_bf16_f32 v206, v188, v189
	v_cvt_pk_bf16_f32 v207, v190, v191
	v_add_u32_e32 v9, 0x8000, v9
	global_store_dwordx4 v9, v[204:207], s[70:71]
	s_waitcnt vmcnt(0)
	s_waitcnt lgkmcnt(0)
	ds_write_b32 v2, v64 offset:0
	ds_write_b32 v2, v65 offset:8
	ds_write_b32 v2, v66 offset:16
	ds_write_b32 v2, v67 offset:24
	ds_write_b32 v2, v68 offset:32
	ds_write_b32 v2, v69 offset:40
	ds_write_b32 v2, v70 offset:48
	ds_write_b32 v2, v71 offset:56
	ds_write_b32 v2, v72 offset:64
	ds_write_b32 v2, v73 offset:72
	ds_write_b32 v2, v74 offset:80
	ds_write_b32 v2, v75 offset:88
	ds_write_b32 v2, v76 offset:96
	ds_write_b32 v2, v77 offset:104
	ds_write_b32 v2, v78 offset:112
	ds_write_b32 v2, v79 offset:120
	ds_write_b32 v2, v80 offset:128
	ds_write_b32 v2, v81 offset:136
	ds_write_b32 v2, v82 offset:144
	ds_write_b32 v2, v83 offset:152
	ds_write_b32 v2, v84 offset:160
	ds_write_b32 v2, v85 offset:168
	ds_write_b32 v2, v86 offset:176
	ds_write_b32 v2, v87 offset:184
	ds_write_b32 v2, v88 offset:192
	ds_write_b32 v2, v89 offset:200
	ds_write_b32 v2, v90 offset:208
	ds_write_b32 v2, v91 offset:216
	ds_write_b32 v2, v92 offset:224
	ds_write_b32 v2, v93 offset:232
	ds_write_b32 v2, v94 offset:240
	ds_write_b32 v2, v95 offset:248
	s_lshr_b32 s70, s67, 2
	s_lshl_b32 s70, s70, 8
	s_and_b32 s71, s67, 3
	s_lshl_b32 s71, s71, 5
	s_add_i32 s70, s70, s71
	s_add_i32 s70, s70, s40
	s_lshl_b32 s70, s70, 12
	s_lshl_b32 s71, s55, 7
	s_add_i32 s70, s70, s71
	s_add_u32 s70, s70, 0x2200000
	s_add_u32 s70, s26, s70
	s_addc_u32 s71, s27, 0
	s_waitcnt lgkmcnt(0)
	ds_read_b64 v[160:161], v3 offset:0
	ds_read_b64 v[162:163], v3 offset:8
	ds_read_b64 v[164:165], v3 offset:16
	ds_read_b64 v[166:167], v3 offset:24
	ds_read_b64 v[168:169], v3 offset:2112
	ds_read_b64 v[170:171], v3 offset:2120
	ds_read_b64 v[172:173], v3 offset:2128
	ds_read_b64 v[174:175], v3 offset:2136
	ds_read_b64 v[176:177], v3 offset:4224
	ds_read_b64 v[178:179], v3 offset:4232
	ds_read_b64 v[180:181], v3 offset:4240
	ds_read_b64 v[182:183], v3 offset:4248
	ds_read_b64 v[184:185], v3 offset:6336
	ds_read_b64 v[186:187], v3 offset:6344
	ds_read_b64 v[188:189], v3 offset:6352
	ds_read_b64 v[190:191], v3 offset:6360
	s_waitcnt lgkmcnt(12)
	v_mul_f32_e32 v160, v160, v104
	v_mul_f32_e32 v161, v161, v105
	v_mul_f32_e32 v162, v162, v106
	v_mul_f32_e32 v163, v163, v107
	v_mul_f32_e32 v164, v164, v108
	v_mul_f32_e32 v165, v165, v109
	v_mul_f32_e32 v166, v166, v110
	v_mul_f32_e32 v167, v167, v111
	v_cvt_pk_bf16_f32 v192, v160, v161
	v_cvt_pk_bf16_f32 v193, v162, v163
	v_cvt_pk_bf16_f32 v194, v164, v165
	v_cvt_pk_bf16_f32 v195, v166, v167
	v_mov_b32_e32 v9, v4
	global_store_dwordx4 v9, v[192:195], s[70:71]
	s_waitcnt lgkmcnt(8)
	v_mul_f32_e32 v168, v168, v104
	v_mul_f32_e32 v169, v169, v105
	v_mul_f32_e32 v170, v170, v106
	v_mul_f32_e32 v171, v171, v107
	v_mul_f32_e32 v172, v172, v108
	v_mul_f32_e32 v173, v173, v109
	v_mul_f32_e32 v174, v174, v110
	v_mul_f32_e32 v175, v175, v111
	v_cvt_pk_bf16_f32 v196, v168, v169
	v_cvt_pk_bf16_f32 v197, v170, v171
	v_cvt_pk_bf16_f32 v198, v172, v173
	v_cvt_pk_bf16_f32 v199, v174, v175
	v_add_u32_e32 v9, 0x8000, v9
	global_store_dwordx4 v9, v[196:199], s[70:71]
	s_waitcnt lgkmcnt(4)
	v_mul_f32_e32 v176, v176, v104
	v_mul_f32_e32 v177, v177, v105
	v_mul_f32_e32 v178, v178, v106
	v_mul_f32_e32 v179, v179, v107
	v_mul_f32_e32 v180, v180, v108
	v_mul_f32_e32 v181, v181, v109
	v_mul_f32_e32 v182, v182, v110
	v_mul_f32_e32 v183, v183, v111
	v_cvt_pk_bf16_f32 v200, v176, v177
	v_cvt_pk_bf16_f32 v201, v178, v179
	v_cvt_pk_bf16_f32 v202, v180, v181
	v_cvt_pk_bf16_f32 v203, v182, v183
	v_add_u32_e32 v9, 0x8000, v9
	global_store_dwordx4 v9, v[200:203], s[70:71]
	s_waitcnt lgkmcnt(0)
	v_mul_f32_e32 v184, v184, v104
	v_mul_f32_e32 v185, v185, v105
	v_mul_f32_e32 v186, v186, v106
	v_mul_f32_e32 v187, v187, v107
	v_mul_f32_e32 v188, v188, v108
	v_mul_f32_e32 v189, v189, v109
	v_mul_f32_e32 v190, v190, v110
	v_mul_f32_e32 v191, v191, v111
	v_cvt_pk_bf16_f32 v204, v184, v185
	v_cvt_pk_bf16_f32 v205, v186, v187
	v_cvt_pk_bf16_f32 v206, v188, v189
	v_cvt_pk_bf16_f32 v207, v190, v191
	v_add_u32_e32 v9, 0x8000, v9
	global_store_dwordx4 v9, v[204:207], s[70:71]
	s_waitcnt vmcnt(0) lgkmcnt(0)

.LBB0_475:
	s_cmp_gt_u32 s29, 4
	s_cselect_b64 s[0:1], -1, 0
	s_and_b64 s[0:1], s[36:37], s[0:1]
	s_andn2_b64 vcc, exec, s[0:1]
	s_cbranch_vccnz .LBB0_525
	s_waitcnt vmcnt(0)
	v_cmp_eq_u32_e32 vcc, 0, v208
	s_waitcnt vmcnt(0) lgkmcnt(0)
	s_barrier
	v_readfirstlane_b32 s3, v208
	s_nop 3
	s_lshr_b32 s3, s3, 6
	s_cmp_eq_u32 s3, 0
	s_cbranch_scc1 .Lmy_cv2_end
	v_readlane_b32 s36, v237, 0
	v_readlane_b32 s37, v237, 1
	s_mul_i32 s4, s2, 7
	s_add_i32 s4, s4, s3
	s_add_i32 s4, s4, -1
	s_lshl_b32 s72, s3, 14
	s_mov_b32 s3, s4
	s_nop 4
	s_load_dwordx4 s[60:63], s[36:37], 0x60
	s_load_dwordx2 s[64:65], s[36:37], 0x70
	v_lshrrev_b32_e32 v6, 5, v209
	v_and_b32_e32 v7, 31, v209
	v_mul_u32_u24_e32 v0, 0x1600, v6
	v_add_lshl_u32 v0, v0, v7, 2
	v_lshlrev_b32_e32 v152, 11, v6
	v_add_lshl_u32 v152, v152, v7, 2
	v_mul_u32_u24_e32 v2, 66, v7
	v_add_lshl_u32 v2, v2, v6, 2
	v_add_u32_e32 v2, s72, v2
	v_and_b32_e32 v8, 7, v209
	v_lshrrev_b32_e32 v9, 3, v209
	v_mul_u32_u24_e32 v3, 0x108, v9
	v_lshl_add_u32 v3, v8, 5, v3
	v_add_u32_e32 v3, s72, v3
	v_lshlrev_b32_e32 v4, 12, v9
	v_lshl_add_u32 v4, v8, 4, v4
	v_lshlrev_b32_e32 v5, 5, v8
	s_waitcnt lgkmcnt(0)
	s_add_i32 s66, s3, 7680
	s_cmpk_ge_u32 s66, 0x1600
	s_cselect_b32 s68, s64, s62
	s_cselect_b32 s69, s65, s63
	s_cselect_b32 s54, 128, 0
	s_cselect_b32 s41, 0x1600, 0
	s_sub_u32 s41, s66, s41
	s_mul_hi_u32 s4, s41, 0xba2e8ba3
	s_lshr_b32 s4, s4, 7
	s_mul_i32 s70, s4, 0xb0
	s_sub_u32 s5, s41, s70
	s_mul_i32 s70, s4, 0x160000
	s_lshl_b32 s71, s5, 7
	s_add_u32 s68, s68, s70
	s_addc_u32 s69, s69, 0
	s_add_u32 s68, s68, s71
	s_addc_u32 s69, s69, 0
	v_mov_b32_e32 v1, v0
	global_load_dword v32, v1, s[68:69] nt
	v_add_u32_e32 v1, 0xb000, v1
	global_load_dword v33, v1, s[68:69] nt
	v_add_u32_e32 v1, 0xb000, v1
	global_load_dword v34, v1, s[68:69] nt
	v_add_u32_e32 v1, 0xb000, v1
	global_load_dword v35, v1, s[68:69] nt
	v_add_u32_e32 v1, 0xb000, v1
	global_load_dword v36, v1, s[68:69] nt
	v_add_u32_e32 v1, 0xb000, v1
	global_load_dword v37, v1, s[68:69] nt
	v_add_u32_e32 v1, 0xb000, v1
	global_load_dword v38, v1, s[68:69] nt
	v_add_u32_e32 v1, 0xb000, v1
	global_load_dword v39, v1, s[68:69] nt
	v_add_u32_e32 v1, 0xb000, v1
	global_load_dword v40, v1, s[68:69] nt
	v_add_u32_e32 v1, 0xb000, v1
	global_load_dword v41, v1, s[68:69] nt
	v_add_u32_e32 v1, 0xb000, v1
	global_load_dword v42, v1, s[68:69] nt
	v_add_u32_e32 v1, 0xb000, v1
	global_load_dword v43, v1, s[68:69] nt
	v_add_u32_e32 v1, 0xb000, v1
	global_load_dword v44, v1, s[68:69] nt
	v_add_u32_e32 v1, 0xb000, v1
	global_load_dword v45, v1, s[68:69] nt
	v_add_u32_e32 v1, 0xb000, v1
	global_load_dword v46, v1, s[68:69] nt
	v_add_u32_e32 v1, 0xb000, v1
	global_load_dword v47, v1, s[68:69] nt
	v_add_u32_e32 v1, 0xb000, v1
	global_load_dword v48, v1, s[68:69] nt
	v_add_u32_e32 v1, 0xb000, v1
	global_load_dword v49, v1, s[68:69] nt
	v_add_u32_e32 v1, 0xb000, v1
	global_load_dword v50, v1, s[68:69] nt
	v_add_u32_e32 v1, 0xb000, v1
	global_load_dword v51, v1, s[68:69] nt
	v_add_u32_e32 v1, 0xb000, v1
	global_load_dword v52, v1, s[68:69] nt
	v_add_u32_e32 v1, 0xb000, v1
	global_load_dword v53, v1, s[68:69] nt
	v_add_u32_e32 v1, 0xb000, v1
	global_load_dword v54, v1, s[68:69] nt
	v_add_u32_e32 v1, 0xb000, v1
	global_load_dword v55, v1, s[68:69] nt
	v_add_u32_e32 v1, 0xb000, v1
	global_load_dword v56, v1, s[68:69] nt
	v_add_u32_e32 v1, 0xb000, v1
	global_load_dword v57, v1, s[68:69] nt
	v_add_u32_e32 v1, 0xb000, v1
	global_load_dword v58, v1, s[68:69] nt
	v_add_u32_e32 v1, 0xb000, v1
	global_load_dword v59, v1, s[68:69] nt
	v_add_u32_e32 v1, 0xb000, v1
	global_load_dword v60, v1, s[68:69] nt
	v_add_u32_e32 v1, 0xb000, v1
	global_load_dword v61, v1, s[68:69] nt
	v_add_u32_e32 v1, 0xb000, v1
	global_load_dword v62, v1, s[68:69] nt
	v_add_u32_e32 v1, 0xb000, v1
	global_load_dword v63, v1, s[68:69] nt
	s_lshl_b32 s70, s4, 8
	s_add_u32 s70, s60, s70
	s_addc_u32 s71, s61, 0
	global_load_dwordx4 v[96:99], v5, s[70:71]
	global_load_dwordx4 v[100:103], v5, s[70:71] offset:16
	s_addk_i32 s66, 0x700
	s_cmpk_ge_u32 s66, 0x1600
	s_cselect_b32 s68, s64, s62
	s_cselect_b32 s69, s65, s63
	s_cselect_b32 s40, 128, 0
	s_cselect_b32 s41, 0x1600, 0
	s_sub_u32 s41, s66, s41
	s_mul_hi_u32 s55, s41, 0xba2e8ba3
	s_lshr_b32 s55, s55, 7
	s_mul_i32 s70, s55, 0xb0
	s_sub_u32 s67, s41, s70
	s_mul_i32 s70, s55, 0x160000
	s_lshl_b32 s71, s67, 7
	s_add_u32 s68, s68, s70
	s_addc_u32 s69, s69, 0
	s_add_u32 s68, s68, s71
	s_addc_u32 s69, s69, 0
	v_mov_b32_e32 v1, v0
	global_load_dword v64, v1, s[68:69] nt
	v_add_u32_e32 v1, 0xb000, v1
	global_load_dword v65, v1, s[68:69] nt
	v_add_u32_e32 v1, 0xb000, v1
	global_load_dword v66, v1, s[68:69] nt
	v_add_u32_e32 v1, 0xb000, v1
	global_load_dword v67, v1, s[68:69] nt
	v_add_u32_e32 v1, 0xb000, v1
	global_load_dword v68, v1, s[68:69] nt
	v_add_u32_e32 v1, 0xb000, v1
	global_load_dword v69, v1, s[68:69] nt
	v_add_u32_e32 v1, 0xb000, v1
	global_load_dword v70, v1, s[68:69] nt
	v_add_u32_e32 v1, 0xb000, v1
	global_load_dword v71, v1, s[68:69] nt
	v_add_u32_e32 v1, 0xb000, v1
	global_load_dword v72, v1, s[68:69] nt
	v_add_u32_e32 v1, 0xb000, v1
	global_load_dword v73, v1, s[68:69] nt
	v_add_u32_e32 v1, 0xb000, v1
	global_load_dword v74, v1, s[68:69] nt
	v_add_u32_e32 v1, 0xb000, v1
	global_load_dword v75, v1, s[68:69] nt
	v_add_u32_e32 v1, 0xb000, v1
	global_load_dword v76, v1, s[68:69] nt
	v_add_u32_e32 v1, 0xb000, v1
	global_load_dword v77, v1, s[68:69] nt
	v_add_u32_e32 v1, 0xb000, v1
	global_load_dword v78, v1, s[68:69] nt
	v_add_u32_e32 v1, 0xb000, v1
	global_load_dword v79, v1, s[68:69] nt
	v_add_u32_e32 v1, 0xb000, v1
	global_load_dword v80, v1, s[68:69] nt
	v_add_u32_e32 v1, 0xb000, v1
	global_load_dword v81, v1, s[68:69] nt
	v_add_u32_e32 v1, 0xb000, v1
	global_load_dword v82, v1, s[68:69] nt
	v_add_u32_e32 v1, 0xb000, v1
	global_load_dword v83, v1, s[68:69] nt
	v_add_u32_e32 v1, 0xb000, v1
	global_load_dword v84, v1, s[68:69] nt
	v_add_u32_e32 v1, 0xb000, v1
	global_load_dword v85, v1, s[68:69] nt
	v_add_u32_e32 v1, 0xb000, v1
	global_load_dword v86, v1, s[68:69] nt
	v_add_u32_e32 v1, 0xb000, v1
	global_load_dword v87, v1, s[68:69] nt
	v_add_u32_e32 v1, 0xb000, v1
	global_load_dword v88, v1, s[68:69] nt
	v_add_u32_e32 v1, 0xb000, v1
	global_load_dword v89, v1, s[68:69] nt
	v_add_u32_e32 v1, 0xb000, v1
	global_load_dword v90, v1, s[68:69] nt
	v_add_u32_e32 v1, 0xb000, v1
	global_load_dword v91, v1, s[68:69] nt
	v_add_u32_e32 v1, 0xb000, v1
	global_load_dword v92, v1, s[68:69] nt
	v_add_u32_e32 v1, 0xb000, v1
	global_load_dword v93, v1, s[68:69] nt
	v_add_u32_e32 v1, 0xb000, v1
	global_load_dword v94, v1, s[68:69] nt
	v_add_u32_e32 v1, 0xb000, v1
	global_load_dword v95, v1, s[68:69] nt
	s_lshl_b32 s70, s55, 8
	s_add_u32 s70, s60, s70
	s_addc_u32 s71, s61, 0
	global_load_dwordx4 v[104:107], v5, s[70:71]
	global_load_dwordx4 v[108:111], v5, s[70:71] offset:16
	s_waitcnt vmcnt(34)
	s_waitcnt lgkmcnt(0)
	ds_write_b32 v2, v32 offset:0
	ds_write_b32 v2, v33 offset:8
	ds_write_b32 v2, v34 offset:16
	ds_write_b32 v2, v35 offset:24
	ds_write_b32 v2, v36 offset:32
	ds_write_b32 v2, v37 offset:40
	ds_write_b32 v2, v38 offset:48
	ds_write_b32 v2, v39 offset:56
	ds_write_b32 v2, v40 offset:64
	ds_write_b32 v2, v41 offset:72
	ds_write_b32 v2, v42 offset:80
	ds_write_b32 v2, v43 offset:88
	ds_write_b32 v2, v44 offset:96
	ds_write_b32 v2, v45 offset:104
	ds_write_b32 v2, v46 offset:112
	ds_write_b32 v2, v47 offset:120
	ds_write_b32 v2, v48 offset:128
	ds_write_b32 v2, v49 offset:136
	ds_write_b32 v2, v50 offset:144
	ds_write_b32 v2, v51 offset:152
	ds_write_b32 v2, v52 offset:160
	ds_write_b32 v2, v53 offset:168
	ds_write_b32 v2, v54 offset:176
	ds_write_b32 v2, v55 offset:184
	ds_write_b32 v2, v56 offset:192
	ds_write_b32 v2, v57 offset:200
	ds_write_b32 v2, v58 offset:208
	ds_write_b32 v2, v59 offset:216
	ds_write_b32 v2, v60 offset:224
	ds_write_b32 v2, v61 offset:232
	ds_write_b32 v2, v62 offset:240
	ds_write_b32 v2, v63 offset:248
	s_lshr_b32 s70, s5, 2
	s_lshl_b32 s70, s70, 8
	s_and_b32 s71, s5, 3
	s_lshl_b32 s71, s71, 5
	s_add_i32 s70, s70, s71
	s_add_i32 s70, s70, s54
	s_lshl_b32 s70, s70, 12
	s_lshl_b32 s71, s4, 7
	s_add_i32 s70, s70, s71
	s_add_u32 s70, s70, 0x2200000
	s_add_u32 s70, s26, s70
	s_addc_u32 s71, s27, 0
	s_waitcnt lgkmcnt(0)
	ds_read_b64 v[160:161], v3 offset:0
	ds_read_b64 v[162:163], v3 offset:8
	ds_read_b64 v[164:165], v3 offset:16
	ds_read_b64 v[166:167], v3 offset:24
	ds_read_b64 v[168:169], v3 offset:2112
	ds_read_b64 v[170:171], v3 offset:2120
	ds_read_b64 v[172:173], v3 offset:2128
	ds_read_b64 v[174:175], v3 offset:2136
	ds_read_b64 v[176:177], v3 offset:4224
	ds_read_b64 v[178:179], v3 offset:4232
	ds_read_b64 v[180:181], v3 offset:4240
	ds_read_b64 v[182:183], v3 offset:4248
	ds_read_b64 v[184:185], v3 offset:6336
	ds_read_b64 v[186:187], v3 offset:6344
	ds_read_b64 v[188:189], v3 offset:6352
	ds_read_b64 v[190:191], v3 offset:6360
	s_waitcnt lgkmcnt(12)
	v_mul_f32_e32 v160, v160, v96
	v_mul_f32_e32 v161, v161, v97
	v_mul_f32_e32 v162, v162, v98
	v_mul_f32_e32 v163, v163, v99
	v_mul_f32_e32 v164, v164, v100
	v_mul_f32_e32 v165, v165, v101
	v_mul_f32_e32 v166, v166, v102
	v_mul_f32_e32 v167, v167, v103
	v_cvt_pk_bf16_f32 v192, v160, v161
	v_cvt_pk_bf16_f32 v193, v162, v163
	v_cvt_pk_bf16_f32 v194, v164, v165
	v_cvt_pk_bf16_f32 v195, v166, v167
	v_mov_b32_e32 v9, v4
	global_store_dwordx4 v9, v[192:195], s[70:71]
	s_waitcnt lgkmcnt(8)
	v_mul_f32_e32 v168, v168, v96
	v_mul_f32_e32 v169, v169, v97
	v_mul_f32_e32 v170, v170, v98
	v_mul_f32_e32 v171, v171, v99
	v_mul_f32_e32 v172, v172, v100
	v_mul_f32_e32 v173, v173, v101
	v_mul_f32_e32 v174, v174, v102
	v_mul_f32_e32 v175, v175, v103
	v_cvt_pk_bf16_f32 v196, v168, v169
	v_cvt_pk_bf16_f32 v197, v170, v171
	v_cvt_pk_bf16_f32 v198, v172, v173
	v_cvt_pk_bf16_f32 v199, v174, v175
	v_add_u32_e32 v9, 0x8000, v9
	global_store_dwordx4 v9, v[196:199], s[70:71]
	s_waitcnt lgkmcnt(4)
	v_mul_f32_e32 v176, v176, v96
	v_mul_f32_e32 v177, v177, v97
	v_mul_f32_e32 v178, v178, v98
	v_mul_f32_e32 v179, v179, v99
	v_mul_f32_e32 v180, v180, v100
	v_mul_f32_e32 v181, v181, v101
	v_mul_f32_e32 v182, v182, v102
	v_mul_f32_e32 v183, v183, v103
	v_cvt_pk_bf16_f32 v200, v176, v177
	v_cvt_pk_bf16_f32 v201, v178, v179
	v_cvt_pk_bf16_f32 v202, v180, v181
	v_cvt_pk_bf16_f32 v203, v182, v183
	v_add_u32_e32 v9, 0x8000, v9
	global_store_dwordx4 v9, v[200:203], s[70:71]
	s_waitcnt lgkmcnt(0)
	v_mul_f32_e32 v184, v184, v96
	v_mul_f32_e32 v185, v185, v97
	v_mul_f32_e32 v186, v186, v98
	v_mul_f32_e32 v187, v187, v99
	v_mul_f32_e32 v188, v188, v100
	v_mul_f32_e32 v189, v189, v101
	v_mul_f32_e32 v190, v190, v102
	v_mul_f32_e32 v191, v191, v103
	v_cvt_pk_bf16_f32 v204, v184, v185
	v_cvt_pk_bf16_f32 v205, v186, v187
	v_cvt_pk_bf16_f32 v206, v188, v189
	v_cvt_pk_bf16_f32 v207, v190, v191
	v_add_u32_e32 v9, 0x8000, v9
	global_store_dwordx4 v9, v[204:207], s[70:71]
	s_waitcnt vmcnt(0)
	s_waitcnt lgkmcnt(0)
	ds_write_b32 v2, v64 offset:0
	ds_write_b32 v2, v65 offset:8
	ds_write_b32 v2, v66 offset:16
	ds_write_b32 v2, v67 offset:24
	ds_write_b32 v2, v68 offset:32
	ds_write_b32 v2, v69 offset:40
	ds_write_b32 v2, v70 offset:48
	ds_write_b32 v2, v71 offset:56
	ds_write_b32 v2, v72 offset:64
	ds_write_b32 v2, v73 offset:72
	ds_write_b32 v2, v74 offset:80
	ds_write_b32 v2, v75 offset:88
	ds_write_b32 v2, v76 offset:96
	ds_write_b32 v2, v77 offset:104
	ds_write_b32 v2, v78 offset:112
	ds_write_b32 v2, v79 offset:120
	ds_write_b32 v2, v80 offset:128
	ds_write_b32 v2, v81 offset:136
	ds_write_b32 v2, v82 offset:144
	ds_write_b32 v2, v83 offset:152
	ds_write_b32 v2, v84 offset:160
	ds_write_b32 v2, v85 offset:168
	ds_write_b32 v2, v86 offset:176
	ds_write_b32 v2, v87 offset:184
	ds_write_b32 v2, v88 offset:192
	ds_write_b32 v2, v89 offset:200
	ds_write_b32 v2, v90 offset:208
	ds_write_b32 v2, v91 offset:216
	ds_write_b32 v2, v92 offset:224
	ds_write_b32 v2, v93 offset:232
	ds_write_b32 v2, v94 offset:240
	ds_write_b32 v2, v95 offset:248
	s_lshr_b32 s70, s67, 2
	s_lshl_b32 s70, s70, 8
	s_and_b32 s71, s67, 3
	s_lshl_b32 s71, s71, 5
	s_add_i32 s70, s70, s71
	s_add_i32 s70, s70, s40
	s_lshl_b32 s70, s70, 12
	s_lshl_b32 s71, s55, 7
	s_add_i32 s70, s70, s71
	s_add_u32 s70, s70, 0x2200000
	s_add_u32 s70, s26, s70
	s_addc_u32 s71, s27, 0
	s_waitcnt lgkmcnt(0)
	ds_read_b64 v[160:161], v3 offset:0
	ds_read_b64 v[162:163], v3 offset:8
	ds_read_b64 v[164:165], v3 offset:16
	ds_read_b64 v[166:167], v3 offset:24
	ds_read_b64 v[168:169], v3 offset:2112
	ds_read_b64 v[170:171], v3 offset:2120
	ds_read_b64 v[172:173], v3 offset:2128
	ds_read_b64 v[174:175], v3 offset:2136
	ds_read_b64 v[176:177], v3 offset:4224
	ds_read_b64 v[178:179], v3 offset:4232
	ds_read_b64 v[180:181], v3 offset:4240
	ds_read_b64 v[182:183], v3 offset:4248
	ds_read_b64 v[184:185], v3 offset:6336
	ds_read_b64 v[186:187], v3 offset:6344
	ds_read_b64 v[188:189], v3 offset:6352
	ds_read_b64 v[190:191], v3 offset:6360
	s_waitcnt lgkmcnt(12)
	v_mul_f32_e32 v160, v160, v104
	v_mul_f32_e32 v161, v161, v105
	v_mul_f32_e32 v162, v162, v106
	v_mul_f32_e32 v163, v163, v107
	v_mul_f32_e32 v164, v164, v108
	v_mul_f32_e32 v165, v165, v109
	v_mul_f32_e32 v166, v166, v110
	v_mul_f32_e32 v167, v167, v111
	v_cvt_pk_bf16_f32 v192, v160, v161
	v_cvt_pk_bf16_f32 v193, v162, v163
	v_cvt_pk_bf16_f32 v194, v164, v165
	v_cvt_pk_bf16_f32 v195, v166, v167
	v_mov_b32_e32 v9, v4
	global_store_dwordx4 v9, v[192:195], s[70:71]
	s_waitcnt lgkmcnt(8)
	v_mul_f32_e32 v168, v168, v104
	v_mul_f32_e32 v169, v169, v105
	v_mul_f32_e32 v170, v170, v106
	v_mul_f32_e32 v171, v171, v107
	v_mul_f32_e32 v172, v172, v108
	v_mul_f32_e32 v173, v173, v109
	v_mul_f32_e32 v174, v174, v110
	v_mul_f32_e32 v175, v175, v111
	v_cvt_pk_bf16_f32 v196, v168, v169
	v_cvt_pk_bf16_f32 v197, v170, v171
	v_cvt_pk_bf16_f32 v198, v172, v173
	v_cvt_pk_bf16_f32 v199, v174, v175
	v_add_u32_e32 v9, 0x8000, v9
	global_store_dwordx4 v9, v[196:199], s[70:71]
	s_waitcnt lgkmcnt(4)
	v_mul_f32_e32 v176, v176, v104
	v_mul_f32_e32 v177, v177, v105
	v_mul_f32_e32 v178, v178, v106
	v_mul_f32_e32 v179, v179, v107
	v_mul_f32_e32 v180, v180, v108
	v_mul_f32_e32 v181, v181, v109
	v_mul_f32_e32 v182, v182, v110
	v_mul_f32_e32 v183, v183, v111
	v_cvt_pk_bf16_f32 v200, v176, v177
	v_cvt_pk_bf16_f32 v201, v178, v179
	v_cvt_pk_bf16_f32 v202, v180, v181
	v_cvt_pk_bf16_f32 v203, v182, v183
	v_add_u32_e32 v9, 0x8000, v9
	global_store_dwordx4 v9, v[200:203], s[70:71]
	s_waitcnt lgkmcnt(0)
	v_mul_f32_e32 v184, v184, v104
	v_mul_f32_e32 v185, v185, v105
	v_mul_f32_e32 v186, v186, v106
	v_mul_f32_e32 v187, v187, v107
	v_mul_f32_e32 v188, v188, v108
	v_mul_f32_e32 v189, v189, v109
	v_mul_f32_e32 v190, v190, v110
	v_mul_f32_e32 v191, v191, v111
	v_cvt_pk_bf16_f32 v204, v184, v185
	v_cvt_pk_bf16_f32 v205, v186, v187
	v_cvt_pk_bf16_f32 v206, v188, v189
	v_cvt_pk_bf16_f32 v207, v190, v191
	v_add_u32_e32 v9, 0x8000, v9
	global_store_dwordx4 v9, v[204:207], s[70:71]
	s_waitcnt vmcnt(0) lgkmcnt(0)
